# ctx small-tile GEMM (K=2816): LDS fragment reads of a K step hoisted into distinct registers, counted lgkmcnt before each MFMA
# speedup vs baseline: 1.0569x; 1.0017x over previous
; template <int K>
; DI void gemm_small_tile(unsigned char* lds, const int tid, const u16* __restrict__ A, const u16* __restrict__ Bt,
;                         const int row0, const int col0, const SmallEpi& E) {
;     ...
;     const unsigned char* st = lds + stc * 24576;
;     stc = (stc == 5) ? 0 : stc + 1; stl = (stl == 5) ? 0 : stl + 1;
; #pragma unroll
;     for (int ks = 0; ks < 4; ++ks) {
;       const bf16x8 af = *(const bf16x8*)(st + aoff + (((ks * 2 + hl) ^ swk) << 4));
;       const bf16x8 bf = *(const bf16x8*)(st + boff + (((ks * 2 + hl) ^ swk) << 4));
;       acc = __builtin_amdgcn_mfma_f32_32x32x16_bf16(af, bf, acc, 0, 0, 0);
;     }
.LBB0_803:
	s_add_i32 s5, s19, 1
	s_cmp_lg_u32 s19, 5
	s_cselect_b32 s5, s5, 0
	s_mul_i32 s6, s5, 0x6000
	s_add_i32 s6, s6, 0
	v_add_u32_e32 v0, s6, v34
	v_add_u32_e32 v22, v0, v35
	ds_read_b128 v[164:167], v22
	v_add_u32_e32 v37, s6, v36
	v_add_u32_e32 v38, v37, v35
	ds_read_b128 v[168:171], v38 offset:8192
	v_add_u32_e32 v38, v37, v33
	s_add_i32 s7, s5, 1
	s_cmp_lg_u32 s5, 5
	s_cselect_b32 s19, s7, 0
	s_add_i32 s5, s4, 1
	v_add_u32_e32 v22, v0, v33
	ds_read_b128 v[172:175], v22
	ds_read_b128 v[176:179], v38 offset:8192
	v_add_u32_e32 v38, v37, v32
	s_cmp_lg_u32 s4, 5
	s_cselect_b32 s20, s5, 0
	s_add_i32 s18, s18, 2
	s_add_u32 s2, s2, 0x100
	s_addc_u32 s3, s3, 0
	v_add_u32_e32 v22, v0, v32
	ds_read_b128 v[180:183], v22
	ds_read_b128 v[184:187], v38 offset:8192
	v_add_u32_e32 v0, v0, v31
	s_cmpk_eq_i32 s2, 0x1500
	ds_read_b128 v[188:191], v0
	v_add_u32_e32 v0, v37, v31
	ds_read_b128 v[192:195], v0 offset:8192
	s_waitcnt lgkmcnt(6)
	v_mfma_f32_32x32x16_bf16 v[2:17], v[164:167], v[168:171], v[2:17]
	s_waitcnt lgkmcnt(4)
	v_mfma_f32_32x32x16_bf16 v[2:17], v[172:175], v[176:179], v[2:17]
	s_waitcnt lgkmcnt(2)
	v_mfma_f32_32x32x16_bf16 v[2:17], v[180:183], v[184:187], v[2:17]
	s_waitcnt lgkmcnt(0)
	v_mfma_f32_32x32x16_bf16 v[2:17], v[188:191], v[192:195], v[2:17]
	s_cbranch_scc1 .LBB0_820

; template <int K>
; DI void gemm_small_tile(unsigned char* lds, const int tid, const u16* __restrict__ A, const u16* __restrict__ Bt,
;                         const int row0, const int col0, const SmallEpi& E) {
;     ...
;     if (t + 4 < NT) asm volatile("s_waitcnt vmcnt(12)" ::: "memory");
;     else if (t + 3 < NT) asm volatile("s_waitcnt vmcnt(9)" ::: "memory");
;     else if (t + 2 < NT) asm volatile("s_waitcnt vmcnt(6)" ::: "memory");
;     else if (t + 1 < NT) asm volatile("s_waitcnt vmcnt(3)" ::: "memory");
;     else asm volatile("s_waitcnt vmcnt(0)" ::: "memory");
;     __builtin_amdgcn_s_barrier();
;     if (t + 5 < NT) SM_LOAD(t + 5, stl);
;     const unsigned char* st = lds + stc * 24576;
;     stc = (stc == 5) ? 0 : stc + 1; stl = (stl == 5) ? 0 : stl + 1;
; #pragma unroll
;     for (int ks = 0; ks < 4; ++ks) {
;       const bf16x8 af = *(const bf16x8*)(st + aoff + (((ks * 2 + hl) ^ swk) << 4));
;       const bf16x8 bf = *(const bf16x8*)(st + boff + (((ks * 2 + hl) ^ swk) << 4));
;       acc = __builtin_amdgcn_mfma_f32_32x32x16_bf16(af, bf, acc, 0, 0, 0);
;     }
.LBB0_814:
	s_mul_i32 s6, s19, 0x6000
	s_add_i32 s6, s6, 0
	v_add_u32_e32 v0, s6, v34
	v_add_u32_e32 v37, v0, v35
	ds_read_b128 v[164:167], v37
	v_add_u32_e32 v37, s6, v36
	v_add_u32_e32 v38, v37, v35
	ds_read_b128 v[168:171], v38 offset:8192
	v_add_u32_e32 v38, v0, v33
	s_andn2_b64 vcc, exec, s[4:5]
	s_mov_b64 s[4:5], -1
	ds_read_b128 v[172:175], v38
	v_add_u32_e32 v38, v37, v33
	ds_read_b128 v[176:179], v38 offset:8192
	v_add_u32_e32 v38, v0, v32
	v_add_u32_e32 v0, v0, v31
	ds_read_b128 v[180:183], v38
	v_add_u32_e32 v38, v37, v32
	ds_read_b128 v[184:187], v38 offset:8192
	ds_read_b128 v[188:191], v0
	v_add_u32_e32 v0, v37, v31
	ds_read_b128 v[192:195], v0 offset:8192
	s_waitcnt lgkmcnt(6)
	v_mfma_f32_32x32x16_bf16 v[2:17], v[164:167], v[168:171], v[2:17]
	s_waitcnt lgkmcnt(4)
	v_mfma_f32_32x32x16_bf16 v[2:17], v[172:175], v[176:179], v[2:17]
	s_waitcnt lgkmcnt(2)
	v_mfma_f32_32x32x16_bf16 v[2:17], v[180:183], v[184:187], v[2:17]
	s_waitcnt lgkmcnt(0)
	v_mfma_f32_32x32x16_bf16 v[2:17], v[188:191], v[192:195], v[2:17]
	s_cbranch_vccnz .LBB0_816
	s_waitcnt vmcnt(6)
	s_mov_b64 s[4:5], 0
